# v19 + P3b epilogue: 16 out-norm gain loads hoisted, counted waits (no store waited)
# speedup vs baseline: 1.0276x; 1.0060x over previous
; DI float bflo(unsigned w) { return __uint_as_float(w << 16); }
; DI float bfhi(unsigned w) { return __uint_as_float(w & 0xffff0000u); }
; DI void gla_out_unit(int chunk, const Params& p, LAS unsigned char* lds) {
;     ...
;     float ss = 0.f;
; #pragma unroll
;     for (int vb = 0; vb < 4; ++vb)
; #pragma unroll
;         for (int e = 0; e < 16; ++e) ss += oT[vb][e] * oT[vb][e];
;     ss += __shfl_xor(ss, 32);
;     const float rstd = rsqrtf(ss * (1.0f / 128.0f) + EPS);
;     bf16_t* mix = (bf16_t*)(p.ws + WS_MIX);
; #pragma unroll
;     for (int vb = 0; vb < 4; ++vb)
; #pragma unroll
;         for (int g = 0; g < 4; ++g) { const int v0 = 32 * vb + 8 * g + 4 * hi;
;             const u32x2 gw = gwv[vb][g];
;             const f32x4 gn = *(const f32x4*)(p.gla_og + h * 128 + v0);
;             float r[4] = {bflo(gw.x), bfhi(gw.x), bflo(gw.y), bfhi(gw.y)}; float ov[4];
; #pragma unroll
;             for (int e = 0; e < 4; ++e) { const float sg = r[e] / (1.0f + __expf(-r[e])); ov[e] = oT[vb][4 * g + e] * rstd * gn[e] * sg; }
.LBB0_617:
	s_nop 1
	v_mul_f32_e32 v74, v49, v49
	v_fmac_f32_e32 v74, v48, v48
	v_fmac_f32_e32 v74, v50, v50
	v_fmac_f32_e32 v74, v51, v51
	v_fmac_f32_e32 v74, v52, v52
	v_fmac_f32_e32 v74, v53, v53
	v_fmac_f32_e32 v74, v54, v54
	v_fmac_f32_e32 v74, v55, v55
	v_fmac_f32_e32 v74, v56, v56
	v_fmac_f32_e32 v74, v57, v57
	v_fmac_f32_e32 v74, v58, v58
	v_fmac_f32_e32 v74, v59, v59
	v_fmac_f32_e32 v74, v60, v60
	v_fmac_f32_e32 v74, v61, v61
	v_fmac_f32_e32 v74, v62, v62
	v_fmac_f32_e32 v74, v63, v63
	v_fmac_f32_e32 v74, v32, v32
	v_fmac_f32_e32 v74, v33, v33
	v_fmac_f32_e32 v74, v34, v34
	v_fmac_f32_e32 v74, v35, v35
	v_fmac_f32_e32 v74, v36, v36
	v_fmac_f32_e32 v74, v37, v37
	v_fmac_f32_e32 v74, v38, v38
	v_fmac_f32_e32 v74, v39, v39
	v_fmac_f32_e32 v74, v40, v40
	v_fmac_f32_e32 v74, v41, v41
	v_fmac_f32_e32 v74, v42, v42
	v_fmac_f32_e32 v74, v43, v43
	v_fmac_f32_e32 v74, v44, v44
	v_fmac_f32_e32 v74, v45, v45
	v_fmac_f32_e32 v74, v46, v46
	v_fmac_f32_e32 v74, v47, v47
	v_fmac_f32_e32 v74, v16, v16
	v_fmac_f32_e32 v74, v17, v17
	v_fmac_f32_e32 v74, v18, v18
	v_fmac_f32_e32 v74, v19, v19
	v_fmac_f32_e32 v74, v20, v20
	v_fmac_f32_e32 v74, v21, v21
	v_fmac_f32_e32 v74, v22, v22
	v_fmac_f32_e32 v74, v23, v23
	v_fmac_f32_e32 v74, v24, v24
	v_fmac_f32_e32 v74, v25, v25
	v_fmac_f32_e32 v74, v26, v26
	v_fmac_f32_e32 v74, v27, v27
	v_fmac_f32_e32 v74, v28, v28
	v_fmac_f32_e32 v74, v29, v29
	v_fmac_f32_e32 v74, v30, v30
	v_fmac_f32_e32 v74, v31, v31
	v_fmac_f32_e32 v74, v0, v0
	v_fmac_f32_e32 v74, v1, v1
	v_fmac_f32_e32 v74, v2, v2
	v_fmac_f32_e32 v74, v3, v3
	v_fmac_f32_e32 v74, v4, v4
	v_fmac_f32_e32 v74, v5, v5
	v_pk_mul_f32 v[72:73], v[6:7], v[6:7]
	v_pk_mul_f32 v[70:71], v[8:9], v[8:9]
	v_add_f32_e32 v72, v72, v74
	v_add_f32_e32 v72, v73, v72
	v_add_f32_e32 v70, v70, v72
	v_pk_mul_f32 v[68:69], v[10:11], v[10:11]
	v_add_f32_e32 v70, v71, v70
	v_add_f32_e32 v68, v68, v70
	v_pk_mul_f32 v[66:67], v[12:13], v[12:13]
	v_add_f32_e32 v68, v69, v68
	v_add_f32_e32 v66, v66, v68
	v_pk_mul_f32 v[64:65], v[14:15], v[14:15]
	v_add_f32_e32 v66, v67, v66
	v_add_f32_e32 v64, v64, v66
	v_add_f32_e32 v64, v65, v64
	ds_bpermute_b32 v65, v210, v64
	s_mov_b32 s8, 0x800000
	v_readlane_b32 s36, v254, 0
	v_ashrrev_i32_e32 v199, 31, v198
	v_readlane_b32 s38, v254, 2
	s_waitcnt lgkmcnt(0)
	v_add_f32_e32 v64, v64, v65
	v_fmamk_f32 v64, v64, 0x3c000000, v211
	v_cmp_gt_f32_e32 vcc, s8, v64
	v_mul_f32_e32 v65, 0x4b800000, v64
	v_readlane_b32 s39, v254, 3
	v_cndmask_b32_e32 v64, v64, v65, vcc
	v_rsq_f32_e32 v64, v64
	s_lshl_b64 s[8:9], s[22:23], 2
	s_mov_b64 s[18:19], s[38:39]
	s_add_u32 s20, s18, s8
	v_mul_f32_e32 v65, 0x45800000, v64
	v_cndmask_b32_e32 v68, v64, v65, vcc
	v_lshlrev_b64 v[64:65], 11, v[198:199]
	v_lshl_add_u64 v[64:65], s[76:77], 0, v[64:65]
	s_addc_u32 s21, s19, s9
	v_lshl_add_u64 v[64:65], s[22:23], 1, v[64:65]
	s_mov_b64 s[8:9], 0x16000400
	v_lshlrev_b32_e32 v69, 2, v203
	v_lshl_add_u64 v[70:71], v[64:65], 0, s[8:9]
	global_load_dwordx4 v[84:87], v69, s[20:21]
	global_load_dwordx4 v[88:91], v69, s[20:21] offset:32
	global_load_dwordx4 v[92:95], v69, s[20:21] offset:64
	global_load_dwordx4 v[96:99], v69, s[20:21] offset:96
	global_load_dwordx4 v[100:103], v69, s[20:21] offset:128
	global_load_dwordx4 v[104:107], v69, s[20:21] offset:160
	global_load_dwordx4 v[108:111], v69, s[20:21] offset:192
	global_load_dwordx4 v[112:115], v69, s[20:21] offset:224
	global_load_dwordx4 v[116:119], v69, s[20:21] offset:256
	global_load_dwordx4 v[120:123], v69, s[20:21] offset:288
	global_load_dwordx4 v[124:127], v69, s[20:21] offset:320
	global_load_dwordx4 v[128:131], v69, s[20:21] offset:352
	global_load_dwordx4 v[132:135], v69, s[20:21] offset:384
	global_load_dwordx4 v[136:139], v69, s[20:21] offset:416
	global_load_dwordx4 v[140:143], v69, s[20:21] offset:448
	global_load_dwordx4 v[144:147], v69, s[20:21] offset:480
	v_lshlrev_b32_e32 v74, 16, v200
	v_and_b32_e32 v75, 0xffff0000, v200
	v_mul_f32_e32 v72, 0xbfb8aa3b, v74
	v_mul_f32_e32 v73, 0xbfb8aa3b, v75
	v_exp_f32_e32 v72, v72
	v_exp_f32_e32 v73, v73
	v_pk_mul_f32 v[48:49], v[48:49], v[68:69] op_sel_hi:[1,0]
	v_pk_mul_f32 v[50:51], v[50:51], v[68:69] op_sel_hi:[1,0]
	v_lshlrev_b32_e32 v166, 1, v203
	v_pk_add_f32 v[72:73], v[72:73], 1.0 op_sel_hi:[1,0]
	v_mov_b32_e32 v207, v167
	v_div_scale_f32 v76, s[8:9], v73, v73, v75
	v_rcp_f32_e32 v77, v76
	v_pk_mul_f32 v[52:53], v[52:53], v[68:69] op_sel_hi:[1,0]
	v_pk_mul_f32 v[54:55], v[54:55], v[68:69] op_sel_hi:[1,0]
	v_mov_b32_e32 v205, v167
	v_fma_f32 v78, -v76, v77, 1.0
	v_fmac_f32_e32 v77, v78, v77
	v_div_scale_f32 v78, vcc, v75, v73, v75
	v_mul_f32_e32 v79, v78, v77
	v_fma_f32 v80, -v76, v79, v78
	v_fmac_f32_e32 v79, v80, v77
	v_fma_f32 v76, -v76, v79, v78
	v_div_fmas_f32 v76, v76, v77, v79
	v_div_fixup_f32 v73, v76, v73, v75
	v_div_scale_f32 v75, s[8:9], v72, v72, v74
	v_rcp_f32_e32 v76, v75
	v_pk_mul_f32 v[56:57], v[56:57], v[68:69] op_sel_hi:[1,0]
	v_mov_b32_e32 v203, v167
	v_pk_mul_f32 v[32:33], v[32:33], v[68:69] op_sel_hi:[1,0]
	v_fma_f32 v77, -v75, v76, 1.0
	v_fmac_f32_e32 v76, v77, v76
	v_div_scale_f32 v77, vcc, v74, v72, v74
	v_mul_f32_e32 v78, v77, v76
	v_fma_f32 v79, -v75, v78, v77
	v_fmac_f32_e32 v78, v79, v76
	v_fma_f32 v75, -v75, v78, v77
	v_div_fmas_f32 v75, v75, v76, v78
	v_div_fixup_f32 v72, v75, v72, v74
	v_pk_mul_f32 v[34:35], v[34:35], v[68:69] op_sel_hi:[1,0]
	v_pk_mul_f32 v[36:37], v[36:37], v[68:69] op_sel_hi:[1,0]
	v_pk_mul_f32 v[38:39], v[38:39], v[68:69] op_sel_hi:[1,0]
	v_pk_mul_f32 v[16:17], v[16:17], v[68:69] op_sel_hi:[1,0]
	v_pk_mul_f32 v[18:19], v[18:19], v[68:69] op_sel_hi:[1,0]
	v_pk_mul_f32 v[20:21], v[20:21], v[68:69] op_sel_hi:[1,0]
	v_pk_mul_f32 v[22:23], v[22:23], v[68:69] op_sel_hi:[1,0]
	v_pk_mul_f32 v[0:1], v[0:1], v[68:69] op_sel_hi:[1,0]
	v_pk_mul_f32 v[2:3], v[2:3], v[68:69] op_sel_hi:[1,0]
	v_pk_mul_f32 v[4:5], v[4:5], v[68:69] op_sel_hi:[1,0]
	v_pk_mul_f32 v[6:7], v[6:7], v[68:69] op_sel_hi:[1,0]
	s_add_i32 s12, s12, s92
	s_add_i32 s0, s0, s33
	s_add_i32 s1, s1, s4
	s_cmpk_gt_i32 s12, 0x1ff
	v_readlane_b32 s37, v254, 1
	v_readlane_b32 s40, v254, 4
	v_readlane_b32 s41, v254, 5
	v_readlane_b32 s42, v254, 6
	v_readlane_b32 s43, v254, 7
	v_readlane_b32 s44, v254, 8
	v_readlane_b32 s45, v254, 9
	v_readlane_b32 s46, v254, 10
	v_readlane_b32 s47, v254, 11
	v_readlane_b32 s48, v254, 12
	v_readlane_b32 s49, v254, 13
	v_readlane_b32 s50, v254, 14
	v_readlane_b32 s51, v254, 15
	s_waitcnt vmcnt(15)
; DI unsigned pk2(float lo, float hi) { f32x2 v = {lo, hi}; bf16x2_t b = __builtin_convertvector(v, bf16x2_t); return __builtin_bit_cast(unsigned, b); }
; DI float bflo(unsigned w) { return __uint_as_float(w << 16); }
; DI float bfhi(unsigned w) { return __uint_as_float(w & 0xffff0000u); }
; DI void gla_out_unit(int chunk, const Params& p, LAS unsigned char* lds) {
;     ...
;     for (int vb = 0; vb < 4; ++vb)
; #pragma unroll
;         for (int g = 0; g < 4; ++g) { const int v0 = 32 * vb + 8 * g + 4 * hi;
;             const u32x2 gw = gwv[vb][g];
;             const f32x4 gn = *(const f32x4*)(p.gla_og + h * 128 + v0);
;             float r[4] = {bflo(gw.x), bfhi(gw.x), bflo(gw.y), bfhi(gw.y)}; float ov[4];
; #pragma unroll
;             for (int e = 0; e < 4; ++e) { const float sg = r[e] / (1.0f + __expf(-r[e])); ov[e] = oT[vb][4 * g + e] * rstd * gn[e] * sg; }
;             u32x2 w; w.x = pk2(ov[0], ov[1]); w.y = pk2(ov[2], ov[3]);
;             *(u32x2*)(mix + (size_t)tok * DM + 512 + h * 128 + v0) = w; }
	v_pk_mul_f32 v[48:49], v[84:85], v[48:49]
	s_nop 0
	v_pk_mul_f32 v[48:49], v[72:73], v[48:49]
	v_lshlrev_b32_e32 v72, 16, v201
	v_and_b32_e32 v73, 0xffff0000, v201
	v_mul_f32_e32 v64, 0xbfb8aa3b, v72
	v_mul_f32_e32 v65, 0xbfb8aa3b, v73
	v_exp_f32_e32 v64, v64
	v_exp_f32_e32 v65, v65
	v_pk_mul_f32 v[50:51], v[86:87], v[50:51]
	v_pk_add_f32 v[64:65], v[64:65], 1.0 op_sel_hi:[1,0]
	s_nop 0
	v_div_scale_f32 v74, s[8:9], v65, v65, v73
	v_rcp_f32_e32 v75, v74
	s_nop 0
	v_fma_f32 v76, -v74, v75, 1.0
	v_fmac_f32_e32 v75, v76, v75
	v_div_scale_f32 v76, vcc, v73, v65, v73
	v_mul_f32_e32 v77, v76, v75
	v_fma_f32 v78, -v74, v77, v76
	v_fmac_f32_e32 v77, v78, v75
	v_fma_f32 v74, -v74, v77, v76
	v_div_fmas_f32 v74, v74, v75, v77
	v_div_fixup_f32 v65, v74, v65, v73
	v_div_scale_f32 v73, s[8:9], v64, v64, v72
	v_rcp_f32_e32 v74, v73
	s_nop 0
	v_fma_f32 v75, -v73, v74, 1.0
	v_fmac_f32_e32 v74, v75, v74
	v_div_scale_f32 v75, vcc, v72, v64, v72
	v_mul_f32_e32 v76, v75, v74
	v_fma_f32 v77, -v73, v76, v75
	v_fmac_f32_e32 v76, v77, v74
	v_fma_f32 v73, -v73, v76, v75
	v_div_fmas_f32 v73, v73, v74, v76
	v_div_fixup_f32 v64, v73, v64, v72
	v_pk_mul_f32 v[50:51], v[64:65], v[50:51]
	v_cvt_pk_bf16_f32 v64, v48, v49
	v_cvt_pk_bf16_f32 v65, v50, v51
	v_lshl_add_u64 v[48:49], v[70:71], 0, v[166:167]
	global_store_dwordx2 v[48:49], v[64:65], off
	v_lshl_add_u64 v[50:51], v[206:207], 2, s[20:21]
	v_lshlrev_b32_e32 v72, 16, v196
	v_and_b32_e32 v73, 0xffff0000, v196
	v_mul_f32_e32 v50, 0xbfb8aa3b, v72
	v_mul_f32_e32 v51, 0xbfb8aa3b, v73
	v_exp_f32_e32 v50, v50
	v_exp_f32_e32 v51, v51
	s_waitcnt vmcnt(15)
	v_pk_mul_f32 v[52:53], v[88:89], v[52:53]
	v_pk_add_f32 v[50:51], v[50:51], 1.0 op_sel_hi:[1,0]
	v_lshlrev_b32_e32 v64, 16, v197
	v_div_scale_f32 v74, s[8:9], v51, v51, v73
	v_rcp_f32_e32 v75, v74
	v_and_b32_e32 v65, 0xffff0000, v197
	v_pk_mul_f32 v[54:55], v[90:91], v[54:55]
	v_fma_f32 v76, -v74, v75, 1.0
	v_fmac_f32_e32 v75, v76, v75
	v_div_scale_f32 v76, vcc, v73, v51, v73
	v_mul_f32_e32 v77, v76, v75
	v_fma_f32 v78, -v74, v77, v76
	v_fmac_f32_e32 v77, v78, v75
	v_fma_f32 v74, -v74, v77, v76
	v_div_fmas_f32 v74, v74, v75, v77
	v_div_fixup_f32 v51, v74, v51, v73
	v_div_scale_f32 v73, s[8:9], v50, v50, v72
	v_rcp_f32_e32 v74, v73
	s_nop 0
	v_fma_f32 v75, -v73, v74, 1.0
	v_fmac_f32_e32 v74, v75, v74
	v_div_scale_f32 v75, vcc, v72, v50, v72
	v_mul_f32_e32 v76, v75, v74
	v_fma_f32 v77, -v73, v76, v75
	v_fmac_f32_e32 v76, v77, v74
	v_fma_f32 v73, -v73, v76, v75
	v_div_fmas_f32 v73, v73, v74, v76
	v_div_fixup_f32 v50, v73, v50, v72
	v_pk_mul_f32 v[50:51], v[50:51], v[52:53]
	v_mul_f32_e32 v52, 0xbfb8aa3b, v64
	v_mul_f32_e32 v53, 0xbfb8aa3b, v65
	v_exp_f32_e32 v52, v52
	v_exp_f32_e32 v53, v53
	v_cvt_pk_bf16_f32 v50, v50, v51
	v_pk_add_f32 v[52:53], v[52:53], 1.0 op_sel_hi:[1,0]
	s_nop 0
	v_div_scale_f32 v72, s[8:9], v53, v53, v65
	v_rcp_f32_e32 v73, v72
	s_nop 0
	v_fma_f32 v74, -v72, v73, 1.0
	v_fmac_f32_e32 v73, v74, v73
	v_div_scale_f32 v74, vcc, v65, v53, v65
	v_mul_f32_e32 v75, v74, v73
	v_fma_f32 v76, -v72, v75, v74
	v_fmac_f32_e32 v75, v76, v73
	v_fma_f32 v72, -v72, v75, v74
	v_div_fmas_f32 v72, v72, v73, v75
	v_div_fixup_f32 v53, v72, v53, v65
	v_div_scale_f32 v65, s[8:9], v52, v52, v64
	v_rcp_f32_e32 v72, v65
	s_nop 0
	v_fma_f32 v73, -v65, v72, 1.0
	v_fmac_f32_e32 v72, v73, v72
	v_div_scale_f32 v73, vcc, v64, v52, v64
	v_mul_f32_e32 v74, v73, v72
	v_fma_f32 v75, -v65, v74, v73
	v_fmac_f32_e32 v74, v75, v72
	v_fma_f32 v65, -v65, v74, v73
	v_div_fmas_f32 v65, v65, v72, v74
	v_div_fixup_f32 v52, v65, v52, v64
	v_pk_mul_f32 v[52:53], v[52:53], v[54:55]
	v_lshlrev_b32_e32 v64, 16, v194
	v_cvt_pk_bf16_f32 v51, v52, v53
	v_lshl_add_u64 v[52:53], v[206:207], 1, v[70:71]
	global_store_dwordx2 v[52:53], v[50:51], off
	v_lshl_add_u64 v[50:51], v[204:205], 2, s[20:21]
	v_and_b32_e32 v65, 0xffff0000, v194
	v_mul_f32_e32 v54, 0xbfb8aa3b, v64
	v_mul_f32_e32 v55, 0xbfb8aa3b, v65
	v_exp_f32_e32 v54, v54
	v_exp_f32_e32 v55, v55
	s_waitcnt vmcnt(15)
	v_pk_mul_f32 v[50:51], v[92:93], v[56:57]
	v_pk_add_f32 v[54:55], v[54:55], 1.0 op_sel_hi:[1,0]
	v_lshlrev_b32_e32 v56, 16, v195
	v_div_scale_f32 v66, s[8:9], v55, v55, v65
	v_rcp_f32_e32 v67, v66
	v_and_b32_e32 v57, 0xffff0000, v195
	v_fma_f32 v72, -v66, v67, 1.0
	v_fmac_f32_e32 v67, v72, v67
	v_div_scale_f32 v72, vcc, v65, v55, v65
	v_mul_f32_e32 v73, v72, v67
	v_fma_f32 v74, -v66, v73, v72
	v_fmac_f32_e32 v73, v74, v67
	v_fma_f32 v66, -v66, v73, v72
	v_div_fmas_f32 v66, v66, v67, v73
	v_div_fixup_f32 v55, v66, v55, v65
	v_div_scale_f32 v65, s[8:9], v54, v54, v64
	v_rcp_f32_e32 v66, v65
	s_nop 0
	v_fma_f32 v67, -v65, v66, 1.0
	v_fmac_f32_e32 v66, v67, v66
	v_div_scale_f32 v67, vcc, v64, v54, v64
	v_mul_f32_e32 v72, v67, v66
	v_fma_f32 v73, -v65, v72, v67
	v_fmac_f32_e32 v72, v73, v66
	v_fma_f32 v65, -v65, v72, v67
	v_div_fmas_f32 v65, v65, v66, v72
	v_div_fixup_f32 v54, v65, v54, v64
	v_pk_mul_f32 v[50:51], v[54:55], v[50:51]
	v_mul_f32_e32 v54, 0xbfb8aa3b, v56
	v_mul_f32_e32 v55, 0xbfb8aa3b, v57
	v_exp_f32_e32 v54, v54
	v_exp_f32_e32 v55, v55
	v_cvt_pk_bf16_f32 v50, v50, v51
	v_pk_add_f32 v[54:55], v[54:55], 1.0 op_sel_hi:[1,0]
	s_nop 0
	v_div_scale_f32 v64, s[8:9], v55, v55, v57
	v_rcp_f32_e32 v65, v64
	s_nop 0
	v_fma_f32 v66, -v64, v65, 1.0
	v_fmac_f32_e32 v65, v66, v65
	v_div_scale_f32 v66, vcc, v57, v55, v57
	v_mul_f32_e32 v67, v66, v65
	v_fma_f32 v72, -v64, v67, v66
	v_fmac_f32_e32 v67, v72, v65
	v_fma_f32 v64, -v64, v67, v66
	v_div_fmas_f32 v64, v64, v65, v67
	v_div_fixup_f32 v55, v64, v55, v57
	v_div_scale_f32 v57, s[8:9], v54, v54, v56
	v_rcp_f32_e32 v64, v57
	s_nop 0
	v_fma_f32 v65, -v57, v64, 1.0
	v_fmac_f32_e32 v64, v65, v64
; DI unsigned pk2(float lo, float hi) { f32x2 v = {lo, hi}; bf16x2_t b = __builtin_convertvector(v, bf16x2_t); return __builtin_bit_cast(unsigned, b); }
; DI float bflo(unsigned w) { return __uint_as_float(w << 16); }
; DI float bfhi(unsigned w) { return __uint_as_float(w & 0xffff0000u); }
; DI void gla_out_unit(int chunk, const Params& p, LAS unsigned char* lds) {
;     ...
;     for (int vb = 0; vb < 4; ++vb)
; #pragma unroll
;         for (int g = 0; g < 4; ++g) { const int v0 = 32 * vb + 8 * g + 4 * hi;
;             const u32x2 gw = gwv[vb][g];
;             const f32x4 gn = *(const f32x4*)(p.gla_og + h * 128 + v0);
;             float r[4] = {bflo(gw.x), bfhi(gw.x), bflo(gw.y), bfhi(gw.y)}; float ov[4];
; #pragma unroll
;             for (int e = 0; e < 4; ++e) { const float sg = r[e] / (1.0f + __expf(-r[e])); ov[e] = oT[vb][4 * g + e] * rstd * gn[e] * sg; }
;             u32x2 w; w.x = pk2(ov[0], ov[1]); w.y = pk2(ov[2], ov[3]);
;             *(u32x2*)(mix + (size_t)tok * DM + 512 + h * 128 + v0) = w; }
	v_div_scale_f32 v65, vcc, v56, v54, v56
	v_mul_f32_e32 v66, v65, v64
	v_fma_f32 v67, -v57, v66, v65
	v_fmac_f32_e32 v66, v67, v64
	v_fma_f32 v57, -v57, v66, v65
	v_div_fmas_f32 v57, v57, v64, v66
	v_div_fixup_f32 v54, v57, v54, v56
	v_pk_mul_f32 v[56:57], v[58:59], v[68:69] op_sel_hi:[1,0]
	s_nop 0
	v_pk_mul_f32 v[52:53], v[94:95], v[56:57]
	v_lshlrev_b32_e32 v56, 16, v192
	v_pk_mul_f32 v[52:53], v[54:55], v[52:53]
	v_and_b32_e32 v57, 0xffff0000, v192
	v_cvt_pk_bf16_f32 v51, v52, v53
	v_lshl_add_u64 v[52:53], v[204:205], 1, v[70:71]
	global_store_dwordx2 v[52:53], v[50:51], off
	v_lshl_add_u64 v[50:51], v[202:203], 2, s[20:21]
	v_mul_f32_e32 v54, 0xbfb8aa3b, v56
	v_mul_f32_e32 v55, 0xbfb8aa3b, v57
	v_exp_f32_e32 v54, v54
	v_exp_f32_e32 v55, v55
	s_nop 0
	v_pk_add_f32 v[54:55], v[54:55], 1.0 op_sel_hi:[1,0]
	s_nop 0
	v_div_scale_f32 v58, s[8:9], v55, v55, v57
	v_rcp_f32_e32 v59, v58
	s_nop 0
	v_fma_f32 v64, -v58, v59, 1.0
	v_fmac_f32_e32 v59, v64, v59
	v_div_scale_f32 v64, vcc, v57, v55, v57
	v_mul_f32_e32 v65, v64, v59
	v_fma_f32 v66, -v58, v65, v64
	v_fmac_f32_e32 v65, v66, v59
	v_fma_f32 v58, -v58, v65, v64
	v_div_fmas_f32 v58, v58, v59, v65
	v_div_fixup_f32 v55, v58, v55, v57
	v_div_scale_f32 v57, s[8:9], v54, v54, v56
	v_rcp_f32_e32 v58, v57
	s_nop 0
	v_fma_f32 v59, -v57, v58, 1.0
	v_fmac_f32_e32 v58, v59, v58
	v_div_scale_f32 v59, vcc, v56, v54, v56
	v_mul_f32_e32 v64, v59, v58
	v_fma_f32 v65, -v57, v64, v59
	v_fmac_f32_e32 v64, v65, v58
	v_fma_f32 v57, -v57, v64, v59
	v_div_fmas_f32 v57, v57, v58, v64
	v_div_fixup_f32 v54, v57, v54, v56
	v_pk_mul_f32 v[56:57], v[60:61], v[68:69] op_sel_hi:[1,0]
	s_waitcnt vmcnt(15)
	v_pk_mul_f32 v[50:51], v[96:97], v[56:57]
	v_lshlrev_b32_e32 v56, 16, v193
	v_and_b32_e32 v57, 0xffff0000, v193
	v_pk_mul_f32 v[50:51], v[54:55], v[50:51]
	v_mul_f32_e32 v54, 0xbfb8aa3b, v56
	v_mul_f32_e32 v55, 0xbfb8aa3b, v57
	v_exp_f32_e32 v54, v54
	v_exp_f32_e32 v55, v55
	v_cvt_pk_bf16_f32 v50, v50, v51
	v_pk_add_f32 v[54:55], v[54:55], 1.0 op_sel_hi:[1,0]
	s_nop 0
	v_div_scale_f32 v58, s[8:9], v55, v55, v57
	v_rcp_f32_e32 v59, v58
	s_nop 0
	v_fma_f32 v60, -v58, v59, 1.0
	v_fmac_f32_e32 v59, v60, v59
	v_div_scale_f32 v60, vcc, v57, v55, v57
	v_mul_f32_e32 v61, v60, v59
	v_fma_f32 v64, -v58, v61, v60
	v_fmac_f32_e32 v61, v64, v59
	v_fma_f32 v58, -v58, v61, v60
	v_div_fmas_f32 v58, v58, v59, v61
	v_div_fixup_f32 v55, v58, v55, v57
	v_div_scale_f32 v57, s[8:9], v54, v54, v56
	v_rcp_f32_e32 v58, v57
	s_nop 0
	v_fma_f32 v59, -v57, v58, 1.0
	v_fmac_f32_e32 v58, v59, v58
	v_div_scale_f32 v59, vcc, v56, v54, v56
	v_mul_f32_e32 v60, v59, v58
	v_fma_f32 v61, -v57, v60, v59
	v_fmac_f32_e32 v60, v61, v58
	v_fma_f32 v57, -v57, v60, v59
	v_div_fmas_f32 v57, v57, v58, v60
	v_div_fixup_f32 v54, v57, v54, v56
	v_pk_mul_f32 v[56:57], v[62:63], v[68:69] op_sel_hi:[1,0]
	s_nop 0
	v_pk_mul_f32 v[52:53], v[98:99], v[56:57]
	v_lshlrev_b32_e32 v56, 16, v190
	v_pk_mul_f32 v[52:53], v[54:55], v[52:53]
	v_and_b32_e32 v57, 0xffff0000, v190
	v_cvt_pk_bf16_f32 v51, v52, v53
	v_lshl_add_u64 v[52:53], v[202:203], 1, v[70:71]
	global_store_dwordx2 v[52:53], v[50:51], off
	v_mul_f32_e32 v54, 0xbfb8aa3b, v56
	v_mul_f32_e32 v55, 0xbfb8aa3b, v57
	v_exp_f32_e32 v54, v54
	v_exp_f32_e32 v55, v55
	s_waitcnt vmcnt(15)
	v_pk_mul_f32 v[32:33], v[100:101], v[32:33]
	v_pk_add_f32 v[54:55], v[54:55], 1.0 op_sel_hi:[1,0]
	v_pk_mul_f32 v[34:35], v[102:103], v[34:35]
	v_div_scale_f32 v58, s[8:9], v55, v55, v57
	v_rcp_f32_e32 v59, v58
	v_lshlrev_b32_e32 v52, 16, v188
	v_and_b32_e32 v53, 0xffff0000, v188
	v_fma_f32 v60, -v58, v59, 1.0
	v_fmac_f32_e32 v59, v60, v59
	v_div_scale_f32 v60, vcc, v57, v55, v57
	v_mul_f32_e32 v61, v60, v59
	v_fma_f32 v62, -v58, v61, v60
	v_fmac_f32_e32 v61, v62, v59
	v_fma_f32 v58, -v58, v61, v60
	v_div_fmas_f32 v58, v58, v59, v61
	v_div_fixup_f32 v55, v58, v55, v57
	v_div_scale_f32 v57, s[8:9], v54, v54, v56
	v_rcp_f32_e32 v58, v57
	s_nop 0
	v_fma_f32 v59, -v57, v58, 1.0
	v_fmac_f32_e32 v58, v59, v58
	v_div_scale_f32 v59, vcc, v56, v54, v56
	v_mul_f32_e32 v60, v59, v58
	v_fma_f32 v61, -v57, v60, v59
	v_fmac_f32_e32 v60, v61, v58
	v_fma_f32 v57, -v57, v60, v59
	v_div_fmas_f32 v57, v57, v58, v60
	v_div_fixup_f32 v54, v57, v54, v56
	v_pk_mul_f32 v[32:33], v[54:55], v[32:33]
	v_lshlrev_b32_e32 v54, 16, v191
	v_and_b32_e32 v55, 0xffff0000, v191
	v_mul_f32_e32 v50, 0xbfb8aa3b, v54
	v_mul_f32_e32 v51, 0xbfb8aa3b, v55
	v_exp_f32_e32 v50, v50
	v_exp_f32_e32 v51, v51
	v_cvt_pk_bf16_f32 v32, v32, v33
	v_pk_add_f32 v[50:51], v[50:51], 1.0 op_sel_hi:[1,0]
	s_nop 0
	v_div_scale_f32 v56, s[8:9], v51, v51, v55
	v_rcp_f32_e32 v57, v56
	s_nop 0
	v_fma_f32 v58, -v56, v57, 1.0
	v_fmac_f32_e32 v57, v58, v57
	v_div_scale_f32 v58, vcc, v55, v51, v55
	v_mul_f32_e32 v59, v58, v57
	v_fma_f32 v60, -v56, v59, v58
	v_fmac_f32_e32 v59, v60, v57
	v_fma_f32 v56, -v56, v59, v58
	v_div_fmas_f32 v56, v56, v57, v59
	v_div_fixup_f32 v51, v56, v51, v55
	v_div_scale_f32 v55, s[8:9], v50, v50, v54
	v_rcp_f32_e32 v56, v55
	s_nop 0
	v_fma_f32 v57, -v55, v56, 1.0
	v_fmac_f32_e32 v56, v57, v56
	v_div_scale_f32 v57, vcc, v54, v50, v54
	v_mul_f32_e32 v58, v57, v56
	v_fma_f32 v59, -v55, v58, v57
	v_fmac_f32_e32 v58, v59, v56
	v_fma_f32 v55, -v55, v58, v57
	v_div_fmas_f32 v55, v55, v56, v58
	v_div_fixup_f32 v50, v55, v50, v54
	v_pk_mul_f32 v[34:35], v[50:51], v[34:35]
	v_mul_f32_e32 v50, 0xbfb8aa3b, v52
	v_cvt_pk_bf16_f32 v33, v34, v35
	global_store_dwordx2 v[48:49], v[32:33], off offset:64
	v_mul_f32_e32 v51, 0xbfb8aa3b, v53
	v_exp_f32_e32 v50, v50
	v_exp_f32_e32 v51, v51
	s_waitcnt vmcnt(15)
; DI unsigned pk2(float lo, float hi) { f32x2 v = {lo, hi}; bf16x2_t b = __builtin_convertvector(v, bf16x2_t); return __builtin_bit_cast(unsigned, b); }
; DI float bflo(unsigned w) { return __uint_as_float(w << 16); }
; DI float bfhi(unsigned w) { return __uint_as_float(w & 0xffff0000u); }
; DI void gla_out_unit(int chunk, const Params& p, LAS unsigned char* lds) {
;     ...
;     for (int vb = 0; vb < 4; ++vb)
; #pragma unroll
;         for (int g = 0; g < 4; ++g) { const int v0 = 32 * vb + 8 * g + 4 * hi;
;             const u32x2 gw = gwv[vb][g];
;             const f32x4 gn = *(const f32x4*)(p.gla_og + h * 128 + v0);
;             float r[4] = {bflo(gw.x), bfhi(gw.x), bflo(gw.y), bfhi(gw.y)}; float ov[4];
; #pragma unroll
;             for (int e = 0; e < 4; ++e) { const float sg = r[e] / (1.0f + __expf(-r[e])); ov[e] = oT[vb][4 * g + e] * rstd * gn[e] * sg; }
;             u32x2 w; w.x = pk2(ov[0], ov[1]); w.y = pk2(ov[2], ov[3]);
;             *(u32x2*)(mix + (size_t)tok * DM + 512 + h * 128 + v0) = w; }
	v_pk_mul_f32 v[32:33], v[104:105], v[36:37]
	v_pk_add_f32 v[50:51], v[50:51], 1.0 op_sel_hi:[1,0]
	v_pk_mul_f32 v[34:35], v[106:107], v[38:39]
	v_div_scale_f32 v54, s[8:9], v51, v51, v53
	v_rcp_f32_e32 v55, v54
	v_lshlrev_b32_e32 v38, 16, v186
	v_and_b32_e32 v39, 0xffff0000, v186
	v_fma_f32 v56, -v54, v55, 1.0
	v_fmac_f32_e32 v55, v56, v55
	v_div_scale_f32 v56, vcc, v53, v51, v53
	v_mul_f32_e32 v57, v56, v55
	v_fma_f32 v58, -v54, v57, v56
	v_fmac_f32_e32 v57, v58, v55
	v_fma_f32 v54, -v54, v57, v56
	v_div_fmas_f32 v54, v54, v55, v57
	v_div_fixup_f32 v51, v54, v51, v53
	v_div_scale_f32 v53, s[8:9], v50, v50, v52
	v_rcp_f32_e32 v54, v53
	s_nop 0
	v_fma_f32 v55, -v53, v54, 1.0
	v_fmac_f32_e32 v54, v55, v54
	v_div_scale_f32 v55, vcc, v52, v50, v52
	v_mul_f32_e32 v56, v55, v54
	v_fma_f32 v57, -v53, v56, v55
	v_fmac_f32_e32 v56, v57, v54
	v_fma_f32 v53, -v53, v56, v55
	v_div_fmas_f32 v53, v53, v54, v56
	v_div_fixup_f32 v50, v53, v50, v52
	v_pk_mul_f32 v[32:33], v[50:51], v[32:33]
	v_lshlrev_b32_e32 v50, 16, v189
	v_and_b32_e32 v51, 0xffff0000, v189
	v_mul_f32_e32 v36, 0xbfb8aa3b, v50
	v_mul_f32_e32 v37, 0xbfb8aa3b, v51
	v_exp_f32_e32 v36, v36
	v_exp_f32_e32 v37, v37
	v_cvt_pk_bf16_f32 v32, v32, v33
	v_pk_add_f32 v[36:37], v[36:37], 1.0 op_sel_hi:[1,0]
	s_nop 0
	v_div_scale_f32 v52, s[8:9], v37, v37, v51
	v_rcp_f32_e32 v53, v52
	s_nop 0
	v_fma_f32 v54, -v52, v53, 1.0
	v_fmac_f32_e32 v53, v54, v53
	v_div_scale_f32 v54, vcc, v51, v37, v51
	v_mul_f32_e32 v55, v54, v53
	v_fma_f32 v56, -v52, v55, v54
	v_fmac_f32_e32 v55, v56, v53
	v_fma_f32 v52, -v52, v55, v54
	v_div_fmas_f32 v52, v52, v53, v55
	v_div_fixup_f32 v37, v52, v37, v51
	v_div_scale_f32 v51, s[8:9], v36, v36, v50
	v_rcp_f32_e32 v52, v51
	s_nop 0
	v_fma_f32 v53, -v51, v52, 1.0
	v_fmac_f32_e32 v52, v53, v52
	v_div_scale_f32 v53, vcc, v50, v36, v50
	v_mul_f32_e32 v54, v53, v52
	v_fma_f32 v55, -v51, v54, v53
	v_fmac_f32_e32 v54, v55, v52
	v_fma_f32 v51, -v51, v54, v53
	v_div_fmas_f32 v51, v51, v52, v54
	v_div_fixup_f32 v36, v51, v36, v50
	v_pk_mul_f32 v[34:35], v[36:37], v[34:35]
	v_mul_f32_e32 v36, 0xbfb8aa3b, v38
	v_cvt_pk_bf16_f32 v33, v34, v35
	global_store_dwordx2 v[48:49], v[32:33], off offset:80
	v_mul_f32_e32 v37, 0xbfb8aa3b, v39
	v_exp_f32_e32 v36, v36
	v_exp_f32_e32 v37, v37
	s_nop 0
	v_pk_add_f32 v[36:37], v[36:37], 1.0 op_sel_hi:[1,0]
	s_nop 0
	v_div_scale_f32 v50, s[8:9], v37, v37, v39
	v_rcp_f32_e32 v51, v50
	s_nop 0
	v_fma_f32 v52, -v50, v51, 1.0
	v_fmac_f32_e32 v51, v52, v51
	v_div_scale_f32 v52, vcc, v39, v37, v39
	v_mul_f32_e32 v53, v52, v51
	v_fma_f32 v54, -v50, v53, v52
	v_fmac_f32_e32 v53, v54, v51
	v_fma_f32 v50, -v50, v53, v52
	v_div_fmas_f32 v50, v50, v51, v53
	v_div_fixup_f32 v37, v50, v37, v39
	v_div_scale_f32 v39, s[8:9], v36, v36, v38
	v_rcp_f32_e32 v50, v39
	s_nop 0
	v_fma_f32 v51, -v39, v50, 1.0
	v_fmac_f32_e32 v50, v51, v50
	v_div_scale_f32 v51, vcc, v38, v36, v38
	v_mul_f32_e32 v52, v51, v50
	v_fma_f32 v53, -v39, v52, v51
	v_fmac_f32_e32 v52, v53, v50
	v_fma_f32 v39, -v39, v52, v51
	v_div_fmas_f32 v39, v39, v50, v52
	v_div_fixup_f32 v36, v39, v36, v38
	v_pk_mul_f32 v[38:39], v[40:41], v[68:69] op_sel_hi:[1,0]
	s_waitcnt vmcnt(15)
	v_pk_mul_f32 v[32:33], v[108:109], v[38:39]
	v_lshlrev_b32_e32 v38, 16, v187
	v_and_b32_e32 v39, 0xffff0000, v187
	v_pk_mul_f32 v[32:33], v[36:37], v[32:33]
	v_mul_f32_e32 v36, 0xbfb8aa3b, v38
	v_mul_f32_e32 v37, 0xbfb8aa3b, v39
	v_exp_f32_e32 v36, v36
	v_exp_f32_e32 v37, v37
	v_cvt_pk_bf16_f32 v32, v32, v33
	v_pk_add_f32 v[36:37], v[36:37], 1.0 op_sel_hi:[1,0]
	s_nop 0
	v_div_scale_f32 v40, s[8:9], v37, v37, v39
	v_rcp_f32_e32 v41, v40
	s_nop 0
	v_fma_f32 v50, -v40, v41, 1.0
	v_fmac_f32_e32 v41, v50, v41
	v_div_scale_f32 v50, vcc, v39, v37, v39
	v_mul_f32_e32 v51, v50, v41
	v_fma_f32 v52, -v40, v51, v50
	v_fmac_f32_e32 v51, v52, v41
	v_fma_f32 v40, -v40, v51, v50
	v_div_fmas_f32 v40, v40, v41, v51
	v_div_fixup_f32 v37, v40, v37, v39
	v_div_scale_f32 v39, s[8:9], v36, v36, v38
	v_rcp_f32_e32 v40, v39
	s_nop 0
	v_fma_f32 v41, -v39, v40, 1.0
	v_fmac_f32_e32 v40, v41, v40
	v_div_scale_f32 v41, vcc, v38, v36, v38
	v_mul_f32_e32 v50, v41, v40
	v_fma_f32 v51, -v39, v50, v41
	v_fmac_f32_e32 v50, v51, v40
	v_fma_f32 v39, -v39, v50, v41
	v_div_fmas_f32 v39, v39, v40, v50
	v_div_fixup_f32 v36, v39, v36, v38
	v_pk_mul_f32 v[38:39], v[42:43], v[68:69] op_sel_hi:[1,0]
	s_nop 0
	v_pk_mul_f32 v[34:35], v[110:111], v[38:39]
	v_lshlrev_b32_e32 v38, 16, v184
	v_pk_mul_f32 v[34:35], v[36:37], v[34:35]
	v_and_b32_e32 v39, 0xffff0000, v184
	v_cvt_pk_bf16_f32 v33, v34, v35
	global_store_dwordx2 v[48:49], v[32:33], off offset:96
	v_mul_f32_e32 v36, 0xbfb8aa3b, v38
	v_mul_f32_e32 v37, 0xbfb8aa3b, v39
	v_exp_f32_e32 v36, v36
	v_exp_f32_e32 v37, v37
	s_nop 0
	v_pk_add_f32 v[36:37], v[36:37], 1.0 op_sel_hi:[1,0]
	s_nop 0
	v_div_scale_f32 v40, s[8:9], v37, v37, v39
	v_rcp_f32_e32 v41, v40
	s_nop 0
	v_fma_f32 v42, -v40, v41, 1.0
	v_fmac_f32_e32 v41, v42, v41
	v_div_scale_f32 v42, vcc, v39, v37, v39
	v_mul_f32_e32 v43, v42, v41
	v_fma_f32 v50, -v40, v43, v42
	v_fmac_f32_e32 v43, v50, v41
	v_fma_f32 v40, -v40, v43, v42
	v_div_fmas_f32 v40, v40, v41, v43
	v_div_fixup_f32 v37, v40, v37, v39
	v_div_scale_f32 v39, s[8:9], v36, v36, v38
	v_rcp_f32_e32 v40, v39
	s_nop 0
	v_fma_f32 v41, -v39, v40, 1.0
	v_fmac_f32_e32 v40, v41, v40
	v_div_scale_f32 v41, vcc, v38, v36, v38
	v_mul_f32_e32 v42, v41, v40
	v_fma_f32 v43, -v39, v42, v41
	v_fmac_f32_e32 v42, v43, v40
	v_fma_f32 v39, -v39, v42, v41
	v_div_fmas_f32 v39, v39, v40, v42
	v_div_fixup_f32 v36, v39, v36, v38
	v_pk_mul_f32 v[38:39], v[44:45], v[68:69] op_sel_hi:[1,0]
	s_waitcnt vmcnt(15)
; DI unsigned pk2(float lo, float hi) { f32x2 v = {lo, hi}; bf16x2_t b = __builtin_convertvector(v, bf16x2_t); return __builtin_bit_cast(unsigned, b); }
; DI float bflo(unsigned w) { return __uint_as_float(w << 16); }
; DI float bfhi(unsigned w) { return __uint_as_float(w & 0xffff0000u); }
; DI void gla_out_unit(int chunk, const Params& p, LAS unsigned char* lds) {
;     ...
;     for (int vb = 0; vb < 4; ++vb)
; #pragma unroll
;         for (int g = 0; g < 4; ++g) { const int v0 = 32 * vb + 8 * g + 4 * hi;
;             const u32x2 gw = gwv[vb][g];
;             const f32x4 gn = *(const f32x4*)(p.gla_og + h * 128 + v0);
;             float r[4] = {bflo(gw.x), bfhi(gw.x), bflo(gw.y), bfhi(gw.y)}; float ov[4];
; #pragma unroll
;             for (int e = 0; e < 4; ++e) { const float sg = r[e] / (1.0f + __expf(-r[e])); ov[e] = oT[vb][4 * g + e] * rstd * gn[e] * sg; }
;             u32x2 w; w.x = pk2(ov[0], ov[1]); w.y = pk2(ov[2], ov[3]);
;             *(u32x2*)(mix + (size_t)tok * DM + 512 + h * 128 + v0) = w; }
	v_pk_mul_f32 v[32:33], v[112:113], v[38:39]
	v_lshlrev_b32_e32 v38, 16, v185
	v_and_b32_e32 v39, 0xffff0000, v185
	v_pk_mul_f32 v[32:33], v[36:37], v[32:33]
	v_mul_f32_e32 v36, 0xbfb8aa3b, v38
	v_mul_f32_e32 v37, 0xbfb8aa3b, v39
	v_exp_f32_e32 v36, v36
	v_exp_f32_e32 v37, v37
	v_cvt_pk_bf16_f32 v32, v32, v33
	v_pk_add_f32 v[36:37], v[36:37], 1.0 op_sel_hi:[1,0]
	s_nop 0
	v_div_scale_f32 v40, s[8:9], v37, v37, v39
	v_rcp_f32_e32 v41, v40
	s_nop 0
	v_fma_f32 v42, -v40, v41, 1.0
	v_fmac_f32_e32 v41, v42, v41
	v_div_scale_f32 v42, vcc, v39, v37, v39
	v_mul_f32_e32 v43, v42, v41
	v_fma_f32 v44, -v40, v43, v42
	v_fmac_f32_e32 v43, v44, v41
	v_fma_f32 v40, -v40, v43, v42
	v_div_fmas_f32 v40, v40, v41, v43
	v_div_fixup_f32 v37, v40, v37, v39
	v_div_scale_f32 v39, s[8:9], v36, v36, v38
	v_rcp_f32_e32 v40, v39
	s_nop 0
	v_fma_f32 v41, -v39, v40, 1.0
	v_fmac_f32_e32 v40, v41, v40
	v_div_scale_f32 v41, vcc, v38, v36, v38
	v_mul_f32_e32 v42, v41, v40
	v_fma_f32 v43, -v39, v42, v41
	v_fmac_f32_e32 v42, v43, v40
	v_fma_f32 v39, -v39, v42, v41
	v_div_fmas_f32 v39, v39, v40, v42
	v_div_fixup_f32 v36, v39, v36, v38
	v_pk_mul_f32 v[38:39], v[46:47], v[68:69] op_sel_hi:[1,0]
	s_nop 0
	v_pk_mul_f32 v[34:35], v[114:115], v[38:39]
	v_lshlrev_b32_e32 v38, 16, v182
	v_pk_mul_f32 v[34:35], v[36:37], v[34:35]
	v_and_b32_e32 v39, 0xffff0000, v182
	v_cvt_pk_bf16_f32 v33, v34, v35
	global_store_dwordx2 v[48:49], v[32:33], off offset:112
	v_mul_f32_e32 v36, 0xbfb8aa3b, v38
	v_mul_f32_e32 v37, 0xbfb8aa3b, v39
	v_exp_f32_e32 v36, v36
	v_exp_f32_e32 v37, v37
	s_waitcnt vmcnt(15)
	v_pk_mul_f32 v[16:17], v[116:117], v[16:17]
	v_pk_add_f32 v[36:37], v[36:37], 1.0 op_sel_hi:[1,0]
	v_pk_mul_f32 v[18:19], v[118:119], v[18:19]
	v_div_scale_f32 v40, s[8:9], v37, v37, v39
	v_rcp_f32_e32 v41, v40
	v_lshlrev_b32_e32 v34, 16, v180
	v_and_b32_e32 v35, 0xffff0000, v180
	v_fma_f32 v42, -v40, v41, 1.0
	v_fmac_f32_e32 v41, v42, v41
	v_div_scale_f32 v42, vcc, v39, v37, v39
	v_mul_f32_e32 v43, v42, v41
	v_fma_f32 v44, -v40, v43, v42
	v_fmac_f32_e32 v43, v44, v41
	v_fma_f32 v40, -v40, v43, v42
	v_div_fmas_f32 v40, v40, v41, v43
	v_div_fixup_f32 v37, v40, v37, v39
	v_div_scale_f32 v39, s[8:9], v36, v36, v38
	v_rcp_f32_e32 v40, v39
	s_nop 0
	v_fma_f32 v41, -v39, v40, 1.0
	v_fmac_f32_e32 v40, v41, v40
	v_div_scale_f32 v41, vcc, v38, v36, v38
	v_mul_f32_e32 v42, v41, v40
	v_fma_f32 v43, -v39, v42, v41
	v_fmac_f32_e32 v42, v43, v40
	v_fma_f32 v39, -v39, v42, v41
	v_div_fmas_f32 v39, v39, v40, v42
	v_div_fixup_f32 v36, v39, v36, v38
	v_pk_mul_f32 v[16:17], v[36:37], v[16:17]
	v_lshlrev_b32_e32 v36, 16, v183
	v_and_b32_e32 v37, 0xffff0000, v183
	v_mul_f32_e32 v32, 0xbfb8aa3b, v36
	v_mul_f32_e32 v33, 0xbfb8aa3b, v37
	v_exp_f32_e32 v32, v32
	v_exp_f32_e32 v33, v33
	v_cvt_pk_bf16_f32 v16, v16, v17
	v_pk_add_f32 v[32:33], v[32:33], 1.0 op_sel_hi:[1,0]
	s_nop 0
	v_div_scale_f32 v38, s[8:9], v33, v33, v37
	v_rcp_f32_e32 v39, v38
	s_nop 0
	v_fma_f32 v40, -v38, v39, 1.0
	v_fmac_f32_e32 v39, v40, v39
	v_div_scale_f32 v40, vcc, v37, v33, v37
	v_mul_f32_e32 v41, v40, v39
	v_fma_f32 v42, -v38, v41, v40
	v_fmac_f32_e32 v41, v42, v39
	v_fma_f32 v38, -v38, v41, v40
	v_div_fmas_f32 v38, v38, v39, v41
	v_div_fixup_f32 v33, v38, v33, v37
	v_div_scale_f32 v37, s[8:9], v32, v32, v36
	v_rcp_f32_e32 v38, v37
	s_nop 0
	v_fma_f32 v39, -v37, v38, 1.0
	v_fmac_f32_e32 v38, v39, v38
	v_div_scale_f32 v39, vcc, v36, v32, v36
	v_mul_f32_e32 v40, v39, v38
	v_fma_f32 v41, -v37, v40, v39
	v_fmac_f32_e32 v40, v41, v38
	v_fma_f32 v37, -v37, v40, v39
	v_div_fmas_f32 v37, v37, v38, v40
	v_div_fixup_f32 v32, v37, v32, v36
	v_pk_mul_f32 v[18:19], v[32:33], v[18:19]
	v_mul_f32_e32 v32, 0xbfb8aa3b, v34
	v_cvt_pk_bf16_f32 v17, v18, v19
	global_store_dwordx2 v[48:49], v[16:17], off offset:128
	v_mul_f32_e32 v33, 0xbfb8aa3b, v35
	v_exp_f32_e32 v32, v32
	v_exp_f32_e32 v33, v33
	s_waitcnt vmcnt(15)
	v_pk_mul_f32 v[16:17], v[120:121], v[20:21]
	v_pk_add_f32 v[32:33], v[32:33], 1.0 op_sel_hi:[1,0]
	v_pk_mul_f32 v[18:19], v[122:123], v[22:23]
	v_div_scale_f32 v36, s[8:9], v33, v33, v35
	v_rcp_f32_e32 v37, v36
	v_lshlrev_b32_e32 v22, 16, v178
	v_and_b32_e32 v23, 0xffff0000, v178
	v_fma_f32 v38, -v36, v37, 1.0
	v_fmac_f32_e32 v37, v38, v37
	v_div_scale_f32 v38, vcc, v35, v33, v35
	v_mul_f32_e32 v39, v38, v37
	v_fma_f32 v40, -v36, v39, v38
	v_fmac_f32_e32 v39, v40, v37
	v_fma_f32 v36, -v36, v39, v38
	v_div_fmas_f32 v36, v36, v37, v39
	v_div_fixup_f32 v33, v36, v33, v35
	v_div_scale_f32 v35, s[8:9], v32, v32, v34
	v_rcp_f32_e32 v36, v35
	s_nop 0
	v_fma_f32 v37, -v35, v36, 1.0
	v_fmac_f32_e32 v36, v37, v36
	v_div_scale_f32 v37, vcc, v34, v32, v34
	v_mul_f32_e32 v38, v37, v36
	v_fma_f32 v39, -v35, v38, v37
	v_fmac_f32_e32 v38, v39, v36
	v_fma_f32 v35, -v35, v38, v37
	v_div_fmas_f32 v35, v35, v36, v38
	v_div_fixup_f32 v32, v35, v32, v34
	v_pk_mul_f32 v[16:17], v[32:33], v[16:17]
	v_lshlrev_b32_e32 v32, 16, v181
	v_and_b32_e32 v33, 0xffff0000, v181
	v_mul_f32_e32 v20, 0xbfb8aa3b, v32
	v_mul_f32_e32 v21, 0xbfb8aa3b, v33
	v_exp_f32_e32 v20, v20
	v_exp_f32_e32 v21, v21
	v_cvt_pk_bf16_f32 v16, v16, v17
	v_pk_add_f32 v[20:21], v[20:21], 1.0 op_sel_hi:[1,0]
	s_nop 0
	v_div_scale_f32 v34, s[8:9], v21, v21, v33
	v_rcp_f32_e32 v35, v34
	s_nop 0
	v_fma_f32 v36, -v34, v35, 1.0
	v_fmac_f32_e32 v35, v36, v35
	v_div_scale_f32 v36, vcc, v33, v21, v33
	v_mul_f32_e32 v37, v36, v35
	v_fma_f32 v38, -v34, v37, v36
	v_fmac_f32_e32 v37, v38, v35
	v_fma_f32 v34, -v34, v37, v36
	v_div_fmas_f32 v34, v34, v35, v37
	v_div_fixup_f32 v21, v34, v21, v33
	v_div_scale_f32 v33, s[8:9], v20, v20, v32
	v_rcp_f32_e32 v34, v33
	s_nop 0
	v_fma_f32 v35, -v33, v34, 1.0
	v_fmac_f32_e32 v34, v35, v34
	v_div_scale_f32 v35, vcc, v32, v20, v32
	v_mul_f32_e32 v36, v35, v34
	v_fma_f32 v37, -v33, v36, v35
	v_fmac_f32_e32 v36, v37, v34
	v_fma_f32 v33, -v33, v36, v35
	v_div_fmas_f32 v33, v33, v34, v36
	v_div_fixup_f32 v20, v33, v20, v32
	v_pk_mul_f32 v[18:19], v[20:21], v[18:19]
	v_mul_f32_e32 v20, 0xbfb8aa3b, v22
	v_cvt_pk_bf16_f32 v17, v18, v19
	global_store_dwordx2 v[48:49], v[16:17], off offset:144
	v_mul_f32_e32 v21, 0xbfb8aa3b, v23
	v_exp_f32_e32 v20, v20
	v_exp_f32_e32 v21, v21
	s_nop 0
	v_pk_add_f32 v[20:21], v[20:21], 1.0 op_sel_hi:[1,0]
	s_nop 0
	v_div_scale_f32 v32, s[8:9], v21, v21, v23
	v_rcp_f32_e32 v33, v32
	s_nop 0
	v_fma_f32 v34, -v32, v33, 1.0
	v_fmac_f32_e32 v33, v34, v33
	v_div_scale_f32 v34, vcc, v23, v21, v23
	v_mul_f32_e32 v35, v34, v33
	v_fma_f32 v36, -v32, v35, v34
	v_fmac_f32_e32 v35, v36, v33
	v_fma_f32 v32, -v32, v35, v34
	v_div_fmas_f32 v32, v32, v33, v35
	v_div_fixup_f32 v21, v32, v21, v23
	v_div_scale_f32 v23, s[8:9], v20, v20, v22
	v_rcp_f32_e32 v32, v23
	s_nop 0
	v_fma_f32 v33, -v23, v32, 1.0
	v_fmac_f32_e32 v32, v33, v32
	v_div_scale_f32 v33, vcc, v22, v20, v22
	v_mul_f32_e32 v34, v33, v32
	v_fma_f32 v35, -v23, v34, v33
	v_fmac_f32_e32 v34, v35, v32
	v_fma_f32 v23, -v23, v34, v33
	v_div_fmas_f32 v23, v23, v32, v34
	v_div_fixup_f32 v20, v23, v20, v22
	v_pk_mul_f32 v[22:23], v[24:25], v[68:69] op_sel_hi:[1,0]
	s_waitcnt vmcnt(15)
; DI unsigned pk2(float lo, float hi) { f32x2 v = {lo, hi}; bf16x2_t b = __builtin_convertvector(v, bf16x2_t); return __builtin_bit_cast(unsigned, b); }
; DI float bflo(unsigned w) { return __uint_as_float(w << 16); }
; DI float bfhi(unsigned w) { return __uint_as_float(w & 0xffff0000u); }
; DI void gla_out_unit(int chunk, const Params& p, LAS unsigned char* lds) {
;     ...
;     for (int vb = 0; vb < 4; ++vb)
; #pragma unroll
;         for (int g = 0; g < 4; ++g) { const int v0 = 32 * vb + 8 * g + 4 * hi;
;             const u32x2 gw = gwv[vb][g];
;             const f32x4 gn = *(const f32x4*)(p.gla_og + h * 128 + v0);
;             float r[4] = {bflo(gw.x), bfhi(gw.x), bflo(gw.y), bfhi(gw.y)}; float ov[4];
; #pragma unroll
;             for (int e = 0; e < 4; ++e) { const float sg = r[e] / (1.0f + __expf(-r[e])); ov[e] = oT[vb][4 * g + e] * rstd * gn[e] * sg; }
;             u32x2 w; w.x = pk2(ov[0], ov[1]); w.y = pk2(ov[2], ov[3]);
;             *(u32x2*)(mix + (size_t)tok * DM + 512 + h * 128 + v0) = w; }
	v_pk_mul_f32 v[16:17], v[124:125], v[22:23]
	v_lshlrev_b32_e32 v22, 16, v179
	v_and_b32_e32 v23, 0xffff0000, v179
	v_pk_mul_f32 v[16:17], v[20:21], v[16:17]
	v_mul_f32_e32 v20, 0xbfb8aa3b, v22
	v_mul_f32_e32 v21, 0xbfb8aa3b, v23
	v_exp_f32_e32 v20, v20
	v_exp_f32_e32 v21, v21
	v_cvt_pk_bf16_f32 v16, v16, v17
	v_pk_add_f32 v[20:21], v[20:21], 1.0 op_sel_hi:[1,0]
	s_nop 0
	v_div_scale_f32 v24, s[8:9], v21, v21, v23
	v_rcp_f32_e32 v25, v24
	s_nop 0
	v_fma_f32 v32, -v24, v25, 1.0
	v_fmac_f32_e32 v25, v32, v25
	v_div_scale_f32 v32, vcc, v23, v21, v23
	v_mul_f32_e32 v33, v32, v25
	v_fma_f32 v34, -v24, v33, v32
	v_fmac_f32_e32 v33, v34, v25
	v_fma_f32 v24, -v24, v33, v32
	v_div_fmas_f32 v24, v24, v25, v33
	v_div_fixup_f32 v21, v24, v21, v23
	v_div_scale_f32 v23, s[8:9], v20, v20, v22
	v_rcp_f32_e32 v24, v23
	s_nop 0
	v_fma_f32 v25, -v23, v24, 1.0
	v_fmac_f32_e32 v24, v25, v24
	v_div_scale_f32 v25, vcc, v22, v20, v22
	v_mul_f32_e32 v32, v25, v24
	v_fma_f32 v33, -v23, v32, v25
	v_fmac_f32_e32 v32, v33, v24
	v_fma_f32 v23, -v23, v32, v25
	v_div_fmas_f32 v23, v23, v24, v32
	v_div_fixup_f32 v20, v23, v20, v22
	v_pk_mul_f32 v[22:23], v[26:27], v[68:69] op_sel_hi:[1,0]
	s_nop 0
	v_pk_mul_f32 v[18:19], v[126:127], v[22:23]
	v_lshlrev_b32_e32 v22, 16, v176
	v_pk_mul_f32 v[18:19], v[20:21], v[18:19]
	v_and_b32_e32 v23, 0xffff0000, v176
	v_cvt_pk_bf16_f32 v17, v18, v19
	global_store_dwordx2 v[48:49], v[16:17], off offset:160
	v_mul_f32_e32 v20, 0xbfb8aa3b, v22
	v_mul_f32_e32 v21, 0xbfb8aa3b, v23
	v_exp_f32_e32 v20, v20
	v_exp_f32_e32 v21, v21
	s_nop 0
	v_pk_add_f32 v[20:21], v[20:21], 1.0 op_sel_hi:[1,0]
	s_nop 0
	v_div_scale_f32 v24, s[8:9], v21, v21, v23
	v_rcp_f32_e32 v25, v24
	s_nop 0
	v_fma_f32 v26, -v24, v25, 1.0
	v_fmac_f32_e32 v25, v26, v25
	v_div_scale_f32 v26, vcc, v23, v21, v23
	v_mul_f32_e32 v27, v26, v25
	v_fma_f32 v32, -v24, v27, v26
	v_fmac_f32_e32 v27, v32, v25
	v_fma_f32 v24, -v24, v27, v26
	v_div_fmas_f32 v24, v24, v25, v27
	v_div_fixup_f32 v21, v24, v21, v23
	v_div_scale_f32 v23, s[8:9], v20, v20, v22
	v_rcp_f32_e32 v24, v23
	s_nop 0
	v_fma_f32 v25, -v23, v24, 1.0
	v_fmac_f32_e32 v24, v25, v24
	v_div_scale_f32 v25, vcc, v22, v20, v22
	v_mul_f32_e32 v26, v25, v24
	v_fma_f32 v27, -v23, v26, v25
	v_fmac_f32_e32 v26, v27, v24
	v_fma_f32 v23, -v23, v26, v25
	v_div_fmas_f32 v23, v23, v24, v26
	v_div_fixup_f32 v20, v23, v20, v22
	v_pk_mul_f32 v[22:23], v[28:29], v[68:69] op_sel_hi:[1,0]
	s_waitcnt vmcnt(15)
	v_pk_mul_f32 v[16:17], v[128:129], v[22:23]
	v_lshlrev_b32_e32 v22, 16, v177
	v_and_b32_e32 v23, 0xffff0000, v177
	v_pk_mul_f32 v[16:17], v[20:21], v[16:17]
	v_mul_f32_e32 v20, 0xbfb8aa3b, v22
	v_mul_f32_e32 v21, 0xbfb8aa3b, v23
	v_exp_f32_e32 v20, v20
	v_exp_f32_e32 v21, v21
	v_cvt_pk_bf16_f32 v16, v16, v17
	v_pk_add_f32 v[20:21], v[20:21], 1.0 op_sel_hi:[1,0]
	s_nop 0
	v_div_scale_f32 v24, s[8:9], v21, v21, v23
	v_rcp_f32_e32 v25, v24
	s_nop 0
	v_fma_f32 v26, -v24, v25, 1.0
	v_fmac_f32_e32 v25, v26, v25
	v_div_scale_f32 v26, vcc, v23, v21, v23
	v_mul_f32_e32 v27, v26, v25
	v_fma_f32 v28, -v24, v27, v26
	v_fmac_f32_e32 v27, v28, v25
	v_fma_f32 v24, -v24, v27, v26
	v_div_fmas_f32 v24, v24, v25, v27
	v_div_fixup_f32 v21, v24, v21, v23
	v_div_scale_f32 v23, s[8:9], v20, v20, v22
	v_rcp_f32_e32 v24, v23
	s_nop 0
	v_fma_f32 v25, -v23, v24, 1.0
	v_fmac_f32_e32 v24, v25, v24
	v_div_scale_f32 v25, vcc, v22, v20, v22
	v_mul_f32_e32 v26, v25, v24
	v_fma_f32 v27, -v23, v26, v25
	v_fmac_f32_e32 v26, v27, v24
	v_fma_f32 v23, -v23, v26, v25
	v_div_fmas_f32 v23, v23, v24, v26
	v_div_fixup_f32 v20, v23, v20, v22
	v_pk_mul_f32 v[22:23], v[30:31], v[68:69] op_sel_hi:[1,0]
	s_nop 0
	v_pk_mul_f32 v[18:19], v[130:131], v[22:23]
	v_lshlrev_b32_e32 v22, 16, v174
	v_pk_mul_f32 v[18:19], v[20:21], v[18:19]
	v_and_b32_e32 v23, 0xffff0000, v174
	v_cvt_pk_bf16_f32 v17, v18, v19
	global_store_dwordx2 v[48:49], v[16:17], off offset:176
	v_mul_f32_e32 v20, 0xbfb8aa3b, v22
	v_mul_f32_e32 v21, 0xbfb8aa3b, v23
	v_exp_f32_e32 v20, v20
	v_exp_f32_e32 v21, v21
	s_waitcnt vmcnt(15)
	v_pk_mul_f32 v[0:1], v[132:133], v[0:1]
	v_pk_add_f32 v[20:21], v[20:21], 1.0 op_sel_hi:[1,0]
	v_pk_mul_f32 v[2:3], v[134:135], v[2:3]
	v_div_scale_f32 v24, s[8:9], v21, v21, v23
	v_rcp_f32_e32 v25, v24
	v_lshlrev_b32_e32 v18, 16, v172
	v_and_b32_e32 v19, 0xffff0000, v172
	v_fma_f32 v26, -v24, v25, 1.0
	v_fmac_f32_e32 v25, v26, v25
	v_div_scale_f32 v26, vcc, v23, v21, v23
	v_mul_f32_e32 v27, v26, v25
	v_fma_f32 v28, -v24, v27, v26
	v_fmac_f32_e32 v27, v28, v25
	v_fma_f32 v24, -v24, v27, v26
	v_div_fmas_f32 v24, v24, v25, v27
	v_div_fixup_f32 v21, v24, v21, v23
	v_div_scale_f32 v23, s[8:9], v20, v20, v22
	v_rcp_f32_e32 v24, v23
	s_nop 0
	v_fma_f32 v25, -v23, v24, 1.0
	v_fmac_f32_e32 v24, v25, v24
	v_div_scale_f32 v25, vcc, v22, v20, v22
	v_mul_f32_e32 v26, v25, v24
	v_fma_f32 v27, -v23, v26, v25
	v_fmac_f32_e32 v26, v27, v24
	v_fma_f32 v23, -v23, v26, v25
	v_div_fmas_f32 v23, v23, v24, v26
	v_div_fixup_f32 v20, v23, v20, v22
	v_pk_mul_f32 v[0:1], v[20:21], v[0:1]
	v_lshlrev_b32_e32 v20, 16, v175
	v_and_b32_e32 v21, 0xffff0000, v175
	v_mul_f32_e32 v16, 0xbfb8aa3b, v20
	v_mul_f32_e32 v17, 0xbfb8aa3b, v21
	v_exp_f32_e32 v16, v16
	v_exp_f32_e32 v17, v17
	v_cvt_pk_bf16_f32 v0, v0, v1
	v_pk_add_f32 v[16:17], v[16:17], 1.0 op_sel_hi:[1,0]
	s_nop 0
	v_div_scale_f32 v22, s[8:9], v17, v17, v21
	v_rcp_f32_e32 v23, v22
	s_nop 0
	v_fma_f32 v24, -v22, v23, 1.0
	v_fmac_f32_e32 v23, v24, v23
	v_div_scale_f32 v24, vcc, v21, v17, v21
	v_mul_f32_e32 v25, v24, v23
	v_fma_f32 v26, -v22, v25, v24
	v_fmac_f32_e32 v25, v26, v23
	v_fma_f32 v22, -v22, v25, v24
	v_div_fmas_f32 v22, v22, v23, v25
	v_div_fixup_f32 v17, v22, v17, v21
	v_div_scale_f32 v21, s[8:9], v16, v16, v20
	v_rcp_f32_e32 v22, v21
	s_nop 0
	v_fma_f32 v23, -v21, v22, 1.0
	v_fmac_f32_e32 v22, v23, v22
	v_div_scale_f32 v23, vcc, v20, v16, v20
	v_mul_f32_e32 v24, v23, v22
	v_fma_f32 v25, -v21, v24, v23
	v_fmac_f32_e32 v24, v25, v22
	v_fma_f32 v21, -v21, v24, v23
	v_div_fmas_f32 v21, v21, v22, v24
	v_div_fixup_f32 v16, v21, v16, v20
	v_pk_mul_f32 v[2:3], v[16:17], v[2:3]
	v_mul_f32_e32 v16, 0xbfb8aa3b, v18
	v_cvt_pk_bf16_f32 v1, v2, v3
	global_store_dwordx2 v[48:49], v[0:1], off offset:192
	v_mul_f32_e32 v17, 0xbfb8aa3b, v19
	v_exp_f32_e32 v16, v16
	v_exp_f32_e32 v17, v17
	s_waitcnt vmcnt(15)
; DI unsigned pk2(float lo, float hi) { f32x2 v = {lo, hi}; bf16x2_t b = __builtin_convertvector(v, bf16x2_t); return __builtin_bit_cast(unsigned, b); }
; DI float bflo(unsigned w) { return __uint_as_float(w << 16); }
; DI float bfhi(unsigned w) { return __uint_as_float(w & 0xffff0000u); }
; DI void gla_out_unit(int chunk, const Params& p, LAS unsigned char* lds) {
;     ...
;     for (int vb = 0; vb < 4; ++vb)
; #pragma unroll
;         for (int g = 0; g < 4; ++g) { const int v0 = 32 * vb + 8 * g + 4 * hi;
;             const u32x2 gw = gwv[vb][g];
;             const f32x4 gn = *(const f32x4*)(p.gla_og + h * 128 + v0);
;             float r[4] = {bflo(gw.x), bfhi(gw.x), bflo(gw.y), bfhi(gw.y)}; float ov[4];
; #pragma unroll
;             for (int e = 0; e < 4; ++e) { const float sg = r[e] / (1.0f + __expf(-r[e])); ov[e] = oT[vb][4 * g + e] * rstd * gn[e] * sg; }
;             u32x2 w; w.x = pk2(ov[0], ov[1]); w.y = pk2(ov[2], ov[3]);
;             *(u32x2*)(mix + (size_t)tok * DM + 512 + h * 128 + v0) = w; }
;     __syncthreads();
	v_pk_mul_f32 v[0:1], v[136:137], v[4:5]
	v_pk_add_f32 v[16:17], v[16:17], 1.0 op_sel_hi:[1,0]
	v_pk_mul_f32 v[2:3], v[138:139], v[6:7]
	v_div_scale_f32 v20, s[8:9], v17, v17, v19
	v_rcp_f32_e32 v21, v20
	v_lshlrev_b32_e32 v6, 16, v170
	v_and_b32_e32 v7, 0xffff0000, v170
	v_fma_f32 v22, -v20, v21, 1.0
	v_fmac_f32_e32 v21, v22, v21
	v_div_scale_f32 v22, vcc, v19, v17, v19
	v_mul_f32_e32 v23, v22, v21
	v_fma_f32 v24, -v20, v23, v22
	v_fmac_f32_e32 v23, v24, v21
	v_fma_f32 v20, -v20, v23, v22
	v_div_fmas_f32 v20, v20, v21, v23
	v_div_fixup_f32 v17, v20, v17, v19
	v_div_scale_f32 v19, s[8:9], v16, v16, v18
	v_rcp_f32_e32 v20, v19
	s_nop 0
	v_fma_f32 v21, -v19, v20, 1.0
	v_fmac_f32_e32 v20, v21, v20
	v_div_scale_f32 v21, vcc, v18, v16, v18
	v_mul_f32_e32 v22, v21, v20
	v_fma_f32 v23, -v19, v22, v21
	v_fmac_f32_e32 v22, v23, v20
	v_fma_f32 v19, -v19, v22, v21
	v_div_fmas_f32 v19, v19, v20, v22
	v_div_fixup_f32 v16, v19, v16, v18
	v_pk_mul_f32 v[0:1], v[16:17], v[0:1]
	v_lshlrev_b32_e32 v16, 16, v173
	v_and_b32_e32 v17, 0xffff0000, v173
	v_mul_f32_e32 v4, 0xbfb8aa3b, v16
	v_mul_f32_e32 v5, 0xbfb8aa3b, v17
	v_exp_f32_e32 v4, v4
	v_exp_f32_e32 v5, v5
	v_cvt_pk_bf16_f32 v0, v0, v1
	v_pk_add_f32 v[4:5], v[4:5], 1.0 op_sel_hi:[1,0]
	s_nop 0
	v_div_scale_f32 v18, s[8:9], v5, v5, v17
	v_rcp_f32_e32 v19, v18
	s_nop 0
	v_fma_f32 v20, -v18, v19, 1.0
	v_fmac_f32_e32 v19, v20, v19
	v_div_scale_f32 v20, vcc, v17, v5, v17
	v_mul_f32_e32 v21, v20, v19
	v_fma_f32 v22, -v18, v21, v20
	v_fmac_f32_e32 v21, v22, v19
	v_fma_f32 v18, -v18, v21, v20
	v_div_fmas_f32 v18, v18, v19, v21
	v_div_fixup_f32 v5, v18, v5, v17
	v_div_scale_f32 v17, s[8:9], v4, v4, v16
	v_rcp_f32_e32 v18, v17
	s_nop 0
	v_fma_f32 v19, -v17, v18, 1.0
	v_fmac_f32_e32 v18, v19, v18
	v_div_scale_f32 v19, vcc, v16, v4, v16
	v_mul_f32_e32 v20, v19, v18
	v_fma_f32 v21, -v17, v20, v19
	v_fmac_f32_e32 v20, v21, v18
	v_fma_f32 v17, -v17, v20, v19
	v_div_fmas_f32 v17, v17, v18, v20
	v_div_fixup_f32 v4, v17, v4, v16
	v_pk_mul_f32 v[2:3], v[4:5], v[2:3]
	v_mul_f32_e32 v4, 0xbfb8aa3b, v6
	v_cvt_pk_bf16_f32 v1, v2, v3
	global_store_dwordx2 v[48:49], v[0:1], off offset:208
	v_mul_f32_e32 v5, 0xbfb8aa3b, v7
	v_exp_f32_e32 v4, v4
	v_exp_f32_e32 v5, v5
	s_nop 0
	v_pk_add_f32 v[4:5], v[4:5], 1.0 op_sel_hi:[1,0]
	s_nop 0
	v_div_scale_f32 v16, s[8:9], v5, v5, v7
	v_rcp_f32_e32 v17, v16
	s_nop 0
	v_fma_f32 v18, -v16, v17, 1.0
	v_fmac_f32_e32 v17, v18, v17
	v_div_scale_f32 v18, vcc, v7, v5, v7
	v_mul_f32_e32 v19, v18, v17
	v_fma_f32 v20, -v16, v19, v18
	v_fmac_f32_e32 v19, v20, v17
	v_fma_f32 v16, -v16, v19, v18
	v_div_fmas_f32 v16, v16, v17, v19
	v_div_fixup_f32 v5, v16, v5, v7
	v_div_scale_f32 v7, s[8:9], v4, v4, v6
	v_rcp_f32_e32 v16, v7
	s_nop 0
	v_fma_f32 v17, -v7, v16, 1.0
	v_fmac_f32_e32 v16, v17, v16
	v_div_scale_f32 v17, vcc, v6, v4, v6
	v_mul_f32_e32 v18, v17, v16
	v_fma_f32 v19, -v7, v18, v17
	v_fmac_f32_e32 v18, v19, v16
	v_fma_f32 v7, -v7, v18, v17
	v_div_fmas_f32 v7, v7, v16, v18
	v_div_fixup_f32 v4, v7, v4, v6
	v_pk_mul_f32 v[6:7], v[8:9], v[68:69] op_sel_hi:[1,0]
	s_waitcnt vmcnt(15)
	v_pk_mul_f32 v[0:1], v[140:141], v[6:7]
	v_lshlrev_b32_e32 v6, 16, v171
	v_and_b32_e32 v7, 0xffff0000, v171
	v_pk_mul_f32 v[0:1], v[4:5], v[0:1]
	v_mul_f32_e32 v4, 0xbfb8aa3b, v6
	v_mul_f32_e32 v5, 0xbfb8aa3b, v7
	v_exp_f32_e32 v4, v4
	v_exp_f32_e32 v5, v5
	v_cvt_pk_bf16_f32 v0, v0, v1
	v_pk_add_f32 v[4:5], v[4:5], 1.0 op_sel_hi:[1,0]
	s_nop 0
	v_div_scale_f32 v8, s[8:9], v5, v5, v7
	v_rcp_f32_e32 v9, v8
	s_nop 0
	v_fma_f32 v16, -v8, v9, 1.0
	v_fmac_f32_e32 v9, v16, v9
	v_div_scale_f32 v16, vcc, v7, v5, v7
	v_mul_f32_e32 v17, v16, v9
	v_fma_f32 v18, -v8, v17, v16
	v_fmac_f32_e32 v17, v18, v9
	v_fma_f32 v8, -v8, v17, v16
	v_div_fmas_f32 v8, v8, v9, v17
	v_div_fixup_f32 v5, v8, v5, v7
	v_div_scale_f32 v7, s[8:9], v4, v4, v6
	v_rcp_f32_e32 v8, v7
	s_nop 0
	v_fma_f32 v9, -v7, v8, 1.0
	v_fmac_f32_e32 v8, v9, v8
	v_div_scale_f32 v9, vcc, v6, v4, v6
	v_mul_f32_e32 v16, v9, v8
	v_fma_f32 v17, -v7, v16, v9
	v_fmac_f32_e32 v16, v17, v8
	v_fma_f32 v7, -v7, v16, v9
	v_div_fmas_f32 v7, v7, v8, v16
	v_div_fixup_f32 v4, v7, v4, v6
	v_pk_mul_f32 v[6:7], v[10:11], v[68:69] op_sel_hi:[1,0]
	s_nop 0
	v_pk_mul_f32 v[2:3], v[142:143], v[6:7]
	v_lshlrev_b32_e32 v6, 16, v168
	v_pk_mul_f32 v[2:3], v[4:5], v[2:3]
	v_and_b32_e32 v7, 0xffff0000, v168
	v_cvt_pk_bf16_f32 v1, v2, v3
	global_store_dwordx2 v[48:49], v[0:1], off offset:224
	v_mul_f32_e32 v4, 0xbfb8aa3b, v6
	v_mul_f32_e32 v5, 0xbfb8aa3b, v7
	v_exp_f32_e32 v4, v4
	v_exp_f32_e32 v5, v5
	s_nop 0
	v_pk_add_f32 v[4:5], v[4:5], 1.0 op_sel_hi:[1,0]
	s_nop 0
	v_div_scale_f32 v8, s[8:9], v5, v5, v7
	v_rcp_f32_e32 v9, v8
	s_nop 0
	v_fma_f32 v10, -v8, v9, 1.0
	v_fmac_f32_e32 v9, v10, v9
	v_div_scale_f32 v10, vcc, v7, v5, v7
	v_mul_f32_e32 v11, v10, v9
	v_fma_f32 v16, -v8, v11, v10
	v_fmac_f32_e32 v11, v16, v9
	v_fma_f32 v8, -v8, v11, v10
	v_div_fmas_f32 v8, v8, v9, v11
	v_div_fixup_f32 v5, v8, v5, v7
	v_div_scale_f32 v7, s[8:9], v4, v4, v6
	v_rcp_f32_e32 v8, v7
	s_nop 0
	v_fma_f32 v9, -v7, v8, 1.0
	v_fmac_f32_e32 v8, v9, v8
	v_div_scale_f32 v9, vcc, v6, v4, v6
	v_mul_f32_e32 v10, v9, v8
	v_fma_f32 v11, -v7, v10, v9
	v_fmac_f32_e32 v10, v11, v8
	v_fma_f32 v7, -v7, v10, v9
	v_div_fmas_f32 v7, v7, v8, v10
	v_div_fixup_f32 v4, v7, v4, v6
	v_pk_mul_f32 v[6:7], v[12:13], v[68:69] op_sel_hi:[1,0]
	s_waitcnt vmcnt(15)
	v_pk_mul_f32 v[0:1], v[144:145], v[6:7]
	v_lshlrev_b32_e32 v6, 16, v169
	v_and_b32_e32 v7, 0xffff0000, v169
	v_pk_mul_f32 v[0:1], v[4:5], v[0:1]
	v_mul_f32_e32 v4, 0xbfb8aa3b, v6
	v_mul_f32_e32 v5, 0xbfb8aa3b, v7
	v_exp_f32_e32 v4, v4
	v_exp_f32_e32 v5, v5
	v_cvt_pk_bf16_f32 v0, v0, v1
	v_pk_add_f32 v[4:5], v[4:5], 1.0 op_sel_hi:[1,0]
	s_nop 0
	v_div_scale_f32 v8, s[8:9], v5, v5, v7
	v_rcp_f32_e32 v9, v8
	s_nop 0
	v_fma_f32 v10, -v8, v9, 1.0
	v_fmac_f32_e32 v9, v10, v9
	v_div_scale_f32 v10, vcc, v7, v5, v7
	v_mul_f32_e32 v11, v10, v9
	v_fma_f32 v12, -v8, v11, v10
	v_fmac_f32_e32 v11, v12, v9
	v_fma_f32 v8, -v8, v11, v10
	v_div_fmas_f32 v8, v8, v9, v11
	v_div_fixup_f32 v5, v8, v5, v7
	v_div_scale_f32 v7, s[8:9], v4, v4, v6
	v_rcp_f32_e32 v8, v7
	s_nop 0
	v_fma_f32 v9, -v7, v8, 1.0
	v_fmac_f32_e32 v8, v9, v8
	v_div_scale_f32 v9, vcc, v6, v4, v6
	v_mul_f32_e32 v10, v9, v8
	v_fma_f32 v11, -v7, v10, v9
	v_fmac_f32_e32 v10, v11, v8
	v_fma_f32 v7, -v7, v10, v9
	v_div_fmas_f32 v7, v7, v8, v10
	v_div_fixup_f32 v4, v7, v4, v6
	v_pk_mul_f32 v[6:7], v[14:15], v[68:69] op_sel_hi:[1,0]
	s_nop 0
	v_pk_mul_f32 v[2:3], v[146:147], v[6:7]
	s_nop 0
	v_pk_mul_f32 v[2:3], v[4:5], v[2:3]
	s_nop 0
	v_cvt_pk_bf16_f32 v1, v2, v3
	global_store_dwordx2 v[48:49], v[0:1], off offset:240
	s_barrier
	s_cbranch_scc1 .LBB0_624
